# prologue de-serialisation: the four loads of each residual-stream row requested together with counted waits (were one load per full wait)
# speedup vs baseline: 1.0054x; 1.0018x over previous
.LBB11_70:
	s_cmp_lg_u64 s[28:29], 0
	v_mov_b32_e32 v0, 0
	s_cselect_b64 s[26:27], -1, 0
	s_cmp_eq_u64 s[28:29], 0
	v_lshl_add_u64 v[10:11], v[64:65], 2, s[28:29]
	v_mov_b32_e32 v2, 0
	v_mov_b32_e32 v3, 0
	v_mov_b32_e32 v4, 0
	v_mov_b32_e32 v5, 0
	v_mov_b32_e32 v84, 0
	v_mov_b32_e32 v85, 0
	v_mov_b32_e32 v86, 0
	v_mov_b32_e32 v87, 0
	v_mov_b32_e32 v88, 0
	v_mov_b32_e32 v89, 0
	v_mov_b32_e32 v90, 0
	v_mov_b32_e32 v91, 0
	v_mov_b32_e32 v92, 0
	v_mov_b32_e32 v93, 0
	v_mov_b32_e32 v94, 0
	v_mov_b32_e32 v95, 0
	v_mov_b32_e32 v96, 0
	v_mov_b32_e32 v97, 0
	v_mov_b32_e32 v98, 0
	v_mov_b32_e32 v99, 0
	s_cbranch_scc1 .LBB11_72
	global_load_dwordx4 v[84:87], v[10:11], off
	global_load_dwordx4 v[88:91], v[10:11], off offset:1024
	global_load_dwordx4 v[92:95], v[10:11], off offset:2048
	global_load_dwordx4 v[96:99], v[10:11], off offset:3072
.LBB11_72:
	s_waitcnt vmcnt(3)
	v_mov_b32_e32 v2, v84
	v_mov_b32_e32 v3, v85
	v_mov_b32_e32 v4, v86
	v_mov_b32_e32 v5, v87
	v_cvt_pk_bf16_f32 v26, v2, v3
	v_cvt_pk_bf16_f32 v27, v4, v5
	s_andn2_b64 vcc, exec, s[26:27]
	v_lshlrev_b32_e32 v12, 16, v27
	v_lshlrev_b32_e32 v8, 16, v26
	v_and_b32_e32 v9, 0xffff0000, v26
	v_and_b32_e32 v13, 0xffff0000, v27
	v_sub_f32_e32 v1, v4, v12
	v_sub_f32_e32 v4, v5, v13
	v_sub_f32_e32 v2, v2, v8
	v_sub_f32_e32 v3, v3, v9
	v_cvt_pk_bf16_f32 v28, v2, v3
	v_cvt_pk_bf16_f32 v29, v1, v4
	v_cndmask_b32_e64 v1, 0, 1, s[26:27]
	v_cmp_ne_u32_e64 s[8:9], 1, v1
	v_mov_b32_e32 v1, 0
	v_mov_b32_e32 v2, 0
	v_mov_b32_e32 v3, 0
	s_cbranch_vccnz .LBB11_74
.LBB11_74:
	s_waitcnt vmcnt(2)
	v_mov_b32_e32 v0, v88
	v_mov_b32_e32 v1, v89
	v_mov_b32_e32 v2, v90
	v_mov_b32_e32 v3, v91
	v_cvt_pk_bf16_f32 v18, v0, v1
	v_cvt_pk_bf16_f32 v19, v2, v3
	v_mov_b32_e32 v4, 0
	v_lshlrev_b32_e32 v30, 16, v18
	v_and_b32_e32 v31, 0xffff0000, v18
	v_lshlrev_b32_e32 v32, 16, v19
	v_and_b32_e32 v33, 0xffff0000, v19
	v_sub_f32_e32 v2, v2, v32
	v_sub_f32_e32 v3, v3, v33
	v_sub_f32_e32 v0, v0, v30
	v_sub_f32_e32 v1, v1, v31
	v_cvt_pk_bf16_f32 v20, v0, v1
	v_cvt_pk_bf16_f32 v21, v2, v3
	s_and_b64 vcc, exec, s[8:9]
	v_mov_b32_e32 v0, 0
	v_mov_b32_e32 v1, 0
	v_mov_b32_e32 v2, 0
	v_mov_b32_e32 v3, 0
	s_cbranch_vccnz .LBB11_76
.LBB11_76:
	s_waitcnt vmcnt(1)
	v_mov_b32_e32 v0, v92
	v_mov_b32_e32 v1, v93
	v_mov_b32_e32 v2, v94
	v_mov_b32_e32 v3, v95
	v_cvt_pk_bf16_f32 v22, v0, v1
	v_cvt_pk_bf16_f32 v23, v2, v3
	s_and_b64 vcc, exec, s[8:9]
	v_lshlrev_b32_e32 v34, 16, v22
	v_and_b32_e32 v35, 0xffff0000, v22
	v_lshlrev_b32_e32 v36, 16, v23
	s_waitcnt lgkmcnt(0)
	v_and_b32_e32 v37, 0xffff0000, v23
	v_mov_b32_e32 v5, 0
	v_mov_b32_e32 v6, 0
	v_mov_b32_e32 v7, 0
	v_sub_f32_e32 v2, v2, v36
	v_sub_f32_e32 v3, v3, v37
	v_sub_f32_e32 v0, v0, v34
	v_sub_f32_e32 v1, v1, v35
	v_cvt_pk_bf16_f32 v24, v0, v1
	v_cvt_pk_bf16_f32 v25, v2, v3
	s_cbranch_vccnz .LBB11_78
.LBB11_78:
	v_lshlrev_b32_e32 v0, 16, v28
	v_and_b32_e32 v1, 0xffff0000, v28
	v_lshlrev_b32_e32 v2, 16, v29
	v_and_b32_e32 v3, 0xffff0000, v29
	v_pk_add_f32 v[14:15], v[12:13], v[2:3]
	v_pk_add_f32 v[12:13], v[8:9], v[0:1]
	v_mul_f32_e32 v1, v14, v14
	v_mul_f32_e32 v0, v13, v13
	v_fmac_f32_e32 v0, v12, v12
	v_fmac_f32_e32 v1, v15, v15
	v_add_f32_e32 v45, v0, v1
	v_lshlrev_b32_e32 v0, 16, v20
	v_and_b32_e32 v1, 0xffff0000, v20
	v_lshlrev_b32_e32 v2, 16, v21
	v_and_b32_e32 v3, 0xffff0000, v21
	v_pk_add_f32 v[10:11], v[32:33], v[2:3]
	v_pk_add_f32 v[8:9], v[30:31], v[0:1]
	v_mul_f32_e32 v1, v10, v10
	v_mul_f32_e32 v0, v9, v9
	v_fmac_f32_e32 v0, v8, v8
	v_fmac_f32_e32 v1, v11, v11
	v_add_f32_e32 v0, v0, v1
	v_add_f32_e32 v30, v45, v0
	v_lshlrev_b32_e32 v0, 16, v24
	v_and_b32_e32 v1, 0xffff0000, v24
	v_lshlrev_b32_e32 v2, 16, v25
	v_and_b32_e32 v3, 0xffff0000, v25
	v_pk_add_f32 v[2:3], v[36:37], v[2:3]
	v_pk_add_f32 v[0:1], v[34:35], v[0:1]
	v_mul_f32_e32 v32, v2, v2
	v_mul_f32_e32 v31, v1, v1
	v_fmac_f32_e32 v31, v0, v0
	v_fmac_f32_e32 v32, v3, v3
	v_add_f32_e32 v31, v31, v32
	v_add_f32_e32 v45, v30, v31
	s_waitcnt vmcnt(0)
	v_mov_b32_e32 v4, v96
	v_mov_b32_e32 v5, v97
	v_mov_b32_e32 v6, v98
	v_mov_b32_e32 v7, v99
	v_cvt_pk_bf16_f32 v30, v4, v5
	v_cvt_pk_bf16_f32 v31, v6, v7
	s_nop 0
	v_lshlrev_b32_e32 v34, 16, v30
	v_and_b32_e32 v35, 0xffff0000, v30
	v_lshlrev_b32_e32 v36, 16, v31
	v_and_b32_e32 v37, 0xffff0000, v31
	v_sub_f32_e32 v6, v6, v36
	v_sub_f32_e32 v7, v7, v37
	v_sub_f32_e32 v4, v4, v34
	v_sub_f32_e32 v5, v5, v35
	v_cvt_pk_bf16_f32 v32, v4, v5
	v_cvt_pk_bf16_f32 v33, v6, v7
	s_load_dwordx2 s[26:27], s[0:1], 0x140
	v_lshlrev_b32_e32 v4, 16, v32
	v_and_b32_e32 v5, 0xffff0000, v32
	v_lshlrev_b32_e32 v6, 16, v33
	v_and_b32_e32 v7, 0xffff0000, v33
	v_pk_add_f32 v[6:7], v[36:37], v[6:7]
	v_pk_add_f32 v[4:5], v[34:35], v[4:5]
	v_mul_f32_e32 v35, v6, v6
	v_mul_f32_e32 v34, v5, v5
	v_fmac_f32_e32 v34, v4, v4
	v_fmac_f32_e32 v35, v7, v7
	v_add_f32_e32 v34, v34, v35
	v_add_f32_e32 v34, v45, v34
	ds_bpermute_b32 v35, v38, v34
	s_waitcnt lgkmcnt(0)
	s_cmp_eq_u64 s[26:27], 0
	v_add_f32_e32 v34, v34, v35
	ds_bpermute_b32 v35, v39, v34
	s_waitcnt lgkmcnt(0)
	v_add_f32_e32 v34, v34, v35
	ds_bpermute_b32 v35, v40, v34
	s_waitcnt lgkmcnt(0)
	v_add_f32_e32 v34, v34, v35
	ds_bpermute_b32 v35, v41, v34
	s_waitcnt lgkmcnt(0)
	v_add_f32_e32 v34, v34, v35
	ds_bpermute_b32 v35, v42, v34
	s_waitcnt lgkmcnt(0)
	v_add_f32_e32 v36, v34, v35
	ds_bpermute_b32 v37, v43, v36
	s_cbranch_scc1 .LBB11_83
	s_mov_b64 s[8:9], -1
	s_and_b64 vcc, exec, s[24:25]
	s_cbranch_vccz .LBB11_81
	s_add_i32 s8, s3, 0xffffc400
	s_cmpk_lt_u32 s3, 0x4080
	s_cselect_b32 s10, s8, -1
	s_mov_b64 s[8:9], 0
